# scan chunk step: LDS fragment reads of the MFMA stage issued ahead of the waits (extra fragment registers), same MFMA order
# speedup vs baseline: 1.0054x; 1.0054x over previous
.LBB0_250:
	v_add_u32_e32 v38, v123, v122
	v_add_u32_e32 v0, v121, v122
	ds_read_b128 v[18:21], v38 offset:36864
	ds_read_b128 v[50:53], v0
	ds_read_b128 v[34:37], v38 offset:36896
	ds_read_b128 v[54:57], v0 offset:32
	ds_read_b128 v[40:43], v38 offset:36928
	ds_read_b128 v[58:61], v0 offset:64
	ds_read_b128 v[44:47], v38 offset:36960
	ds_read_b128 v[62:65], v0 offset:96
	s_mov_b64 s[18:19], 0
	v_mov_b32_e32 v228, v143
	v_mov_b32_e32 v229, v142
	v_mov_b32_e32 v230, v141
	ds_read_b128 v[232:235], v143
	ds_read_b128 v[236:239], v143 offset:32
	ds_read_b128 v[240:243], v143 offset:64
	ds_read_b128 v[250:253], v143 offset:96
	s_waitcnt lgkmcnt(10)
	v_mfma_f32_32x32x16_bf16 v[18:33], v[18:21], v[50:53], 0
	s_waitcnt lgkmcnt(8)
	v_mfma_f32_32x32x16_bf16 v[18:33], v[34:37], v[54:57], v[18:33]
	s_waitcnt lgkmcnt(6)
	v_mfma_f32_32x32x16_bf16 v[18:33], v[40:43], v[58:61], v[18:33]
	s_waitcnt lgkmcnt(4)
	v_mfma_f32_32x32x16_bf16 v[18:33], v[44:47], v[62:65], v[18:33]
	s_branch .LBB0_252
.Lhw_scan_kreads:
	ds_read_b128 v[232:235], v228
	ds_read_b128 v[236:239], v228 offset:32
	ds_read_b128 v[240:243], v228 offset:64
	ds_read_b128 v[250:253], v228 offset:96
.LBB0_252:
	v_cmp_eq_u32_e32 vcc, 0, v229
	s_waitcnt lgkmcnt(3)
	v_mfma_f32_32x32x16_bf16 v[34:49], v[232:235], v[50:53], 0
	ds_read2_b64 v[232:235], v230 offset1:2
	s_waitcnt lgkmcnt(3)
	v_mfma_f32_32x32x16_bf16 v[34:49], v[236:239], v[54:57], v[34:49]
	ds_read2_b64 v[236:239], v230 offset0:4 offset1:6
	s_waitcnt lgkmcnt(3)
	v_mfma_f32_32x32x16_bf16 v[34:49], v[240:243], v[58:61], v[34:49]
	s_waitcnt lgkmcnt(2)
	v_mfma_f32_32x32x16_bf16 v[34:49], v[250:253], v[62:65], v[34:49]
	s_and_saveexec_b64 s[20:21], vcc
	s_cbranch_execz .LBB0_251
	s_nop 9
	v_cndmask_b32_e64 v231, v34, 0, s[52:53]
	v_cndmask_b32_e64 v35, 0, v35, s[54:55]
	v_cndmask_b32_e64 v34, v231, v34, s[54:55]
	v_cndmask_b32_e64 v36, v36, 0, s[56:57]
	v_cndmask_b32_e64 v37, v37, 0, s[58:59]
	v_cndmask_b32_e64 v38, v38, 0, s[60:61]
	v_cndmask_b32_e64 v39, v39, 0, s[62:63]
	v_cndmask_b32_e64 v40, v40, 0, s[64:65]
	v_cndmask_b32_e64 v41, v41, 0, s[66:67]
	v_cndmask_b32_e64 v42, v42, 0, s[68:69]
	v_cndmask_b32_e64 v43, v43, 0, s[70:71]
	v_cndmask_b32_e64 v44, v44, 0, s[72:73]
	v_cndmask_b32_e64 v45, v45, 0, s[74:75]
	v_cndmask_b32_e64 v46, v46, 0, s[76:77]
	v_cndmask_b32_e64 v47, v47, 0, s[78:79]
	v_cndmask_b32_e64 v48, v48, 0, s[80:81]
	v_cndmask_b32_e64 v49, v49, 0, s[82:83]
.LBB0_251:
	s_or_b64 exec, exec, s[20:21]
	s_nop 8
	v_cvt_pk_bf16_f32 v34, v34, v35
	v_cvt_pk_bf16_f32 v35, v36, v37
	v_cvt_pk_bf16_f32 v36, v38, v39
	v_cvt_pk_bf16_f32 v37, v40, v41
	v_cvt_pk_bf16_f32 v38, v42, v43
	v_cvt_pk_bf16_f32 v39, v44, v45
	v_cvt_pk_bf16_f32 v40, v46, v47
	v_cvt_pk_bf16_f32 v41, v48, v49
	s_waitcnt lgkmcnt(1)
	v_mfma_f32_32x32x16_bf16 v[18:33], v[232:235], v[34:37], v[18:33]
	v_add_u32_e32 v229, 1, v229
	v_cmp_eq_u32_e32 vcc, 1, v229
	v_add_u32_e32 v230, 64, v230
	s_or_b64 s[18:19], vcc, s[18:19]
	v_add_u32_e32 v228, 0x1200, v228
	s_waitcnt lgkmcnt(0)
	v_mfma_f32_32x32x16_bf16 v[18:33], v[236:239], v[38:41], v[18:33]
	s_andn2_b64 exec, exec, s[18:19]
	s_cbranch_execnz .Lhw_scan_kreads
.LBB0_254:
	s_or_b64 exec, exec, s[18:19]
	ds_read_b32 v48, v145 offset:47104
	ds_read_b128 v[36:39], v146 offset:27648
	ds_read_b128 v[40:43], v0 offset:18432
	ds_read_b128 v[44:47], v146 offset:27680
	ds_read_b128 v[232:235], v0 offset:18464
	ds_read_b128 v[236:239], v146 offset:27712
	ds_read_b128 v[240:243], v0 offset:18496
	ds_read_b128 v[250:253], v146 offset:27744
	v_lshl_or_b32 v34, s12, 6, v120
	v_xad_u32 v35, v34, -1, s26
	v_cndmask_b32_e64 v34, v35, v34, s[84:85]
	v_add_u32_e32 v34, s33, v34
	v_ashrrev_i32_e32 v35, 31, v34
	v_lshlrev_b64 v[34:35], 11, v[34:35]
	v_lshl_add_u64 v[34:35], v[86:87], 0, v[34:35]
	s_nop 1
	v_cvt_pk_bf16_f32 v18, v18, v19
	v_cvt_pk_bf16_f32 v19, v20, v21
	global_store_dwordx2 v[34:35], v[18:19], off
	v_cvt_pk_bf16_f32 v18, v22, v23
	v_cvt_pk_bf16_f32 v19, v24, v25
	global_store_dwordx2 v[34:35], v[18:19], off offset:16
	v_cvt_pk_bf16_f32 v18, v26, v27
	v_cvt_pk_bf16_f32 v19, v28, v29
	global_store_dwordx2 v[34:35], v[18:19], off offset:32
	v_cvt_pk_bf16_f32 v18, v30, v31
	v_cvt_pk_bf16_f32 v19, v32, v33
	global_store_dwordx2 v[34:35], v[18:19], off offset:48
	ds_read_b128 v[18:21], v0 offset:18528
	s_cmp_eq_u32 s13, s35
	s_waitcnt lgkmcnt(8)
	v_pk_mul_f32 v[16:17], v[16:17], v[48:49] op_sel_hi:[1,0]
	v_pk_mul_f32 v[14:15], v[14:15], v[48:49] op_sel_hi:[1,0]
	v_pk_mul_f32 v[12:13], v[12:13], v[48:49] op_sel_hi:[1,0]
	v_pk_mul_f32 v[10:11], v[10:11], v[48:49] op_sel_hi:[1,0]
	v_pk_mul_f32 v[8:9], v[8:9], v[48:49] op_sel_hi:[1,0]
	v_pk_mul_f32 v[6:7], v[6:7], v[48:49] op_sel_hi:[1,0]
	v_pk_mul_f32 v[4:5], v[4:5], v[48:49] op_sel_hi:[1,0]
	v_pk_mul_f32 v[2:3], v[2:3], v[48:49] op_sel_hi:[1,0]
	s_nop 1
	s_waitcnt lgkmcnt(6)
	v_mfma_f32_32x32x16_bf16 v[2:17], v[36:39], v[40:43], v[2:17]
	s_waitcnt lgkmcnt(4)
	v_mfma_f32_32x32x16_bf16 v[2:17], v[44:47], v[232:235], v[2:17]
	s_waitcnt lgkmcnt(2)
	v_mfma_f32_32x32x16_bf16 v[2:17], v[236:239], v[240:243], v[2:17]
	s_waitcnt lgkmcnt(0)
	s_barrier
	v_mfma_f32_32x32x16_bf16 v[2:17], v[250:253], v[18:21], v[2:17]
	s_cbranch_scc1 .LBB0_256
	s_mov_b32 s12, s13
	s_branch .LBB0_215
